# NSA: V^T tiles stored in LDS with per-32-key permutation so V fragments are read with ds_read_b128 instead of bank-conflicted ds_read2_b64
# speedup vs baseline: 1.0088x; 1.0088x over previous
.LBB0_741:
	s_waitcnt lgkmcnt(0)
	v_add_f32_e32 v13, v12, v13
	v_div_scale_f32 v12, s[0:1], v13, v13, 1.0
	v_rcp_f32_e32 v14, v12
	v_div_scale_f32 v15, vcc, 1.0, v13, 1.0
	v_readlane_b32 s0, v254, 47
	v_fma_f32 v16, -v12, v14, 1.0
	v_fmac_f32_e32 v14, v16, v14
	v_mul_f32_e32 v16, v15, v14
	v_fma_f32 v17, -v12, v16, v15
	v_fmac_f32_e32 v16, v17, v14
	v_fma_f32 v12, -v12, v16, v15
	v_div_fmas_f32 v12, v12, v14, v16
	v_div_fixup_f32 v14, v12, v13, 1.0
	v_cmp_lt_f32_e32 vcc, 0, v13
	v_mul_u32_u24_e32 v88, 0x48, v54
	v_readlane_b32 s1, v254, 48
	v_cndmask_b32_e32 v74, 0, v14, vcc
	v_lshl_add_u64 v[14:15], s[88:89], 0, v[44:45]
	v_lshl_add_u64 v[14:15], v[14:15], 0, v[0:1]
	v_lshlrev_b32_e32 v13, 1, v88
	v_lshl_add_u64 v[76:77], s[0:1], 0, v[14:15]
	v_mov_b32_e32 v14, s81
	s_movk_i32 s0, 0x410
	v_mov_b32_e32 v12, 0
	v_add_u32_e32 v118, v58, v13
	v_or_b32_e32 v16, 0x15000, v13
	v_or_b32_e32 v17, 0x15000, v56
	v_add_u32_e32 v119, v57, v13
	v_add_u32_e32 v13, 0x17400, v13
	v_add_u32_e32 v18, 0x17400, v56
	v_lshlrev_b32_e32 v19, 10, v120
	v_mad_u32_u24 v14, v120, s0, v14
	s_movk_i32 s0, 0x1004
	v_add_u32_e32 v116, 0x15000, v55
	v_add_u32_e32 v117, 0x17400, v55
	v_add_u32_e32 v243, 0x4800, v118
	v_add_u32_e32 v244, 0x4800, v119
	v_lshrrev_b32_e32 v245, 3, v194
	v_mul_u32_u24_e32 v245, 0x90, v245
	v_and_b32_e32 v246, 4, v194
	v_lshl_add_u32 v245, v246, 4, v245
	v_and_b32_e32 v246, 1, v194
	v_lshl_add_u32 v245, v246, 5, v245
	v_and_b32_e32 v246, 2, v194
	v_lshl_add_u32 v245, v246, 2, v245
	v_add_u32_e32 v238, 0x15000, v245
	v_add_u32_e32 v242, 0x17400, v245
	s_mov_b32 s14, 0
	v_cmp_eq_u32_e64 s[8:9], 0, v52
	v_mov_b32_e32 v75, v74
	v_sub_u32_e32 v81, 0, v59
	v_add3_u32 v91, v14, v98, s0
	v_add3_u32 v100, s81, v19, v98
	s_mov_b32 s15, 3
	s_movk_i32 s16, 0x7f0
	v_add_u32_e32 v101, v16, v53
	v_add_u32_e32 v102, v17, v53
	v_add_u32_e32 v104, v13, v53
	v_add_u32_e32 v105, v18, v53
	s_mov_b32 s17, 0
	v_mov_b32_e32 v13, v12
	v_mov_b32_e32 v14, v12
	v_mov_b32_e32 v15, v12
	v_mov_b32_e32 v24, v12
	v_mov_b32_e32 v25, v12
	v_mov_b32_e32 v26, v12
	v_mov_b32_e32 v27, v12
	v_mov_b32_e32 v20, v12
	v_mov_b32_e32 v21, v12
	v_mov_b32_e32 v22, v12
	v_mov_b32_e32 v23, v12
	v_mov_b32_e32 v16, v12
	v_mov_b32_e32 v17, v12
	v_mov_b32_e32 v18, v12
	v_mov_b32_e32 v19, v12
	s_waitcnt vmcnt(1)
	ds_write_b128 v112, v[28:31]
	s_waitcnt vmcnt(0)
	ds_write2_b64 v238, v[32:33], v[34:35] offset1:2
	s_waitcnt lgkmcnt(0)
	s_barrier
	s_branch .LBB0_743

.LBB0_759:
	s_or_b64 exec, exec, s[4:5]
	v_cvt_pk_bf16_f32 v48, v52, v53
	v_cvt_pk_bf16_f32 v50, v54, v55
	ds_read_b128 v[52:55], v243
	v_cvt_pk_bf16_f32 v44, v109, v111
	v_cvt_pk_bf16_f32 v45, v78, v79
	v_cvt_pk_bf16_f32 v46, v110, v121
	v_cvt_pk_bf16_f32 v47, v84, v85
	v_cvt_pk_bf16_f32 v49, v56, v57
	v_cvt_pk_bf16_f32 v51, v58, v59
	s_waitcnt lgkmcnt(0)
	v_mfma_f32_16x16x32_bf16 v[12:15], v[52:55], v[44:47], v[12:15]
	ds_read_b128 v[52:55], v243 offset:64
	v_add_u32_e32 v56, 0x800, v102
	s_add_i32 s2, s15, -2
	s_cmp_lt_u32 s2, s12
	s_cselect_b64 s[4:5], -1, 0
	s_cmp_ge_u32 s2, s12
	s_waitcnt lgkmcnt(0)
	v_mfma_f32_16x16x32_bf16 v[12:15], v[52:55], v[48:51], v[12:15]
	ds_read_b128 v[52:55], v243 offset:2304
	s_waitcnt lgkmcnt(0)
	v_mfma_f32_16x16x32_bf16 v[24:27], v[52:55], v[44:47], v[24:27]
	ds_read_b128 v[52:55], v243 offset:2368
	v_add_u32_e32 v56, 0x1000, v102
	s_waitcnt lgkmcnt(0)
	v_mfma_f32_16x16x32_bf16 v[24:27], v[52:55], v[48:51], v[24:27]
	ds_read_b128 v[52:55], v243 offset:4608
	s_waitcnt lgkmcnt(0)
	v_mfma_f32_16x16x32_bf16 v[20:23], v[52:55], v[44:47], v[20:23]
	ds_read_b128 v[52:55], v243 offset:4672
	v_add_u32_e32 v56, 0x1800, v102
	s_waitcnt lgkmcnt(0)
	v_mfma_f32_16x16x32_bf16 v[20:23], v[52:55], v[48:51], v[20:23]
	ds_read_b128 v[52:55], v243 offset:6912
	s_waitcnt lgkmcnt(0)
	v_mfma_f32_16x16x32_bf16 v[16:19], v[52:55], v[44:47], v[16:19]
	ds_read_b128 v[44:47], v243 offset:6976
	s_waitcnt lgkmcnt(0)
	v_mfma_f32_16x16x32_bf16 v[16:19], v[44:47], v[48:51], v[16:19]
	s_cbranch_scc1 .LBB0_761
	s_waitcnt vmcnt(1)
	ds_write_b128 v113, v[36:39]
	s_waitcnt vmcnt(0)
	ds_write2_b64 v242, v[40:41], v[42:43] offset1:2

.LBB0_779:
	s_or_b64 exec, exec, s[4:5]
	v_cvt_pk_bf16_f32 v48, v52, v53
	v_cvt_pk_bf16_f32 v50, v54, v55
	ds_read_b128 v[52:55], v244
	v_cvt_pk_bf16_f32 v44, v109, v111
	v_cvt_pk_bf16_f32 v45, v78, v79
	v_cvt_pk_bf16_f32 v46, v110, v121
	v_cvt_pk_bf16_f32 v47, v84, v85
	v_cvt_pk_bf16_f32 v49, v56, v57
	v_cvt_pk_bf16_f32 v51, v58, v59
	s_waitcnt lgkmcnt(0)
	v_mfma_f32_16x16x32_bf16 v[12:15], v[52:55], v[44:47], v[12:15]
	ds_read_b128 v[52:55], v244 offset:64
	v_add_u32_e32 v56, 0x800, v105
	s_andn2_b64 vcc, exec, s[0:1]
	s_waitcnt lgkmcnt(0)
	v_mfma_f32_16x16x32_bf16 v[12:15], v[52:55], v[48:51], v[12:15]
	ds_read_b128 v[52:55], v244 offset:2304
	s_waitcnt lgkmcnt(0)
	v_mfma_f32_16x16x32_bf16 v[24:27], v[52:55], v[44:47], v[24:27]
	ds_read_b128 v[52:55], v244 offset:2368
	v_add_u32_e32 v56, 0x1000, v105
	s_waitcnt lgkmcnt(0)
	v_mfma_f32_16x16x32_bf16 v[24:27], v[52:55], v[48:51], v[24:27]
	ds_read_b128 v[52:55], v244 offset:4608
	s_waitcnt lgkmcnt(0)
	v_mfma_f32_16x16x32_bf16 v[20:23], v[52:55], v[44:47], v[20:23]
	ds_read_b128 v[52:55], v244 offset:4672
	v_add_u32_e32 v56, 0x1800, v105
	s_waitcnt lgkmcnt(0)
	v_mfma_f32_16x16x32_bf16 v[20:23], v[52:55], v[48:51], v[20:23]
	ds_read_b128 v[52:55], v244 offset:6912
	s_waitcnt lgkmcnt(0)
	v_mfma_f32_16x16x32_bf16 v[16:19], v[52:55], v[44:47], v[16:19]
	ds_read_b128 v[44:47], v244 offset:6976
	s_waitcnt lgkmcnt(0)
	v_mfma_f32_16x16x32_bf16 v[16:19], v[44:47], v[48:51], v[16:19]
	s_cbranch_vccnz .LBB0_742
	s_waitcnt vmcnt(1)
	ds_write_b128 v112, v[28:31]
	s_waitcnt vmcnt(0)
	ds_write2_b64 v238, v[32:33], v[34:35] offset1:2
	s_branch .LBB0_742

.LBB0_965:
	s_waitcnt vmcnt(1)
	ds_write_b128 v112, v[44:47]
	s_waitcnt vmcnt(0)
	ds_write2_b64 v238, v[48:49], v[50:51] offset1:2

.LBB0_976:
	v_cmp_lt_f32_e32 vcc, s37, v76
	v_sub_f32_e32 v76, v76, v109
	v_exp_f32_e32 v76, v76
	s_mov_b64 s[4:5], 0
	v_cndmask_b32_e32 v76, 0, v76, vcc
	v_cmp_lt_f32_e32 vcc, s37, v77
	v_sub_f32_e32 v77, v77, v109
	v_exp_f32_e32 v77, v77
	v_add_f32_e32 v132, 0, v76
	v_cndmask_b32_e32 v77, 0, v77, vcc
	v_cmp_lt_f32_e32 vcc, s37, v78
	v_sub_f32_e32 v78, v78, v109
	v_exp_f32_e32 v78, v78
	v_add_f32_e32 v132, v77, v132
	v_cvt_pk_bf16_f32 v76, v76, v77
	v_cndmask_b32_e32 v78, 0, v78, vcc
	v_cmp_lt_f32_e32 vcc, s37, v79
	v_sub_f32_e32 v79, v79, v109
	v_exp_f32_e32 v79, v79
	v_add_f32_e32 v132, v78, v132
	v_cndmask_b32_e32 v79, 0, v79, vcc
	v_cmp_lt_f32_e32 vcc, s37, v110
	v_sub_f32_e32 v110, v110, v109
	v_exp_f32_e32 v110, v110
	v_add_f32_e32 v132, v79, v132
	v_cvt_pk_bf16_f32 v77, v78, v79
	v_cndmask_b32_e32 v110, 0, v110, vcc
	v_cmp_lt_f32_e32 vcc, s37, v111
	v_sub_f32_e32 v111, v111, v109
	v_exp_f32_e32 v111, v111
	v_add_f32_e32 v132, v110, v132
	v_cndmask_b32_e32 v111, 0, v111, vcc
	v_cmp_lt_f32_e32 vcc, s37, v121
	v_sub_f32_e32 v121, v121, v109
	v_exp_f32_e32 v121, v121
	v_add_f32_e32 v132, v111, v132
	v_cvt_pk_bf16_f32 v78, v110, v111
	v_sub_f32_e32 v110, v123, v109
	v_cndmask_b32_e32 v121, 0, v121, vcc
	v_cmp_lt_f32_e32 vcc, s37, v122
	v_sub_f32_e32 v122, v122, v109
	v_exp_f32_e32 v122, v122
	v_add_f32_e32 v132, v121, v132
	v_exp_f32_e32 v110, v110
	v_cndmask_b32_e32 v122, 0, v122, vcc
	v_cvt_pk_bf16_f32 v79, v121, v122
	v_sub_f32_e32 v121, v124, v109
	v_add_f32_e32 v132, v122, v132
	v_exp_f32_e32 v121, v121
	v_sub_f32_e32 v122, v125, v109
	v_exp_f32_e32 v122, v122
	v_cmp_lt_f32_e32 vcc, s37, v123
	s_nop 1
	v_cndmask_b32_e32 v110, 0, v110, vcc
	v_cmp_lt_f32_e32 vcc, s37, v124
	v_add_f32_e32 v111, v110, v132
	s_nop 0
	v_cndmask_b32_e32 v121, 0, v121, vcc
	v_cmp_lt_f32_e32 vcc, s37, v125
	v_add_f32_e32 v111, v121, v111
	s_nop 0
	v_cndmask_b32_e32 v123, 0, v122, vcc
	v_sub_f32_e32 v122, v126, v109
	v_exp_f32_e32 v122, v122
	v_cmp_lt_f32_e32 vcc, s37, v126
	v_add_f32_e32 v111, v123, v111
	s_nop 0
	v_cndmask_b32_e32 v124, 0, v122, vcc
	v_sub_f32_e32 v122, v127, v109
	v_exp_f32_e32 v122, v122
	v_cmp_lt_f32_e32 vcc, s37, v127
	v_add_f32_e32 v111, v124, v111
	v_cvt_pk_bf16_f32 v123, v123, v124
	v_cndmask_b32_e32 v125, 0, v122, vcc
	v_sub_f32_e32 v122, v128, v109
	v_exp_f32_e32 v122, v122
	v_cmp_lt_f32_e32 vcc, s37, v128
	v_add_f32_e32 v111, v125, v111
	s_nop 0
	v_cndmask_b32_e32 v126, 0, v122, vcc
	v_sub_f32_e32 v122, v129, v109
	v_exp_f32_e32 v122, v122
	v_cmp_lt_f32_e32 vcc, s37, v129
	v_add_f32_e32 v111, v126, v111
	v_cvt_pk_bf16_f32 v124, v125, v126
	v_cndmask_b32_e32 v127, 0, v122, vcc
	v_sub_f32_e32 v122, v130, v109
	v_exp_f32_e32 v122, v122
	v_cmp_lt_f32_e32 vcc, s37, v130
	v_add_f32_e32 v111, v127, v111
	s_nop 0
	v_cndmask_b32_e32 v128, 0, v122, vcc
	v_add_f32_e32 v111, v128, v111
	v_cvt_pk_bf16_f32 v125, v127, v128
	ds_read_b128 v[126:129], v243
	s_waitcnt lgkmcnt(0)
	v_mfma_f32_16x16x32_bf16 v[72:75], v[126:129], v[76:79], v[72:75]
	ds_read_b128 v[126:129], v243 offset:64
	v_cvt_pk_bf16_f32 v122, v110, v121
	v_add_f32_e32 v110, v131, v111
	v_add_u32_e32 v111, 0x800, v81
	s_waitcnt lgkmcnt(0)
	v_mfma_f32_16x16x32_bf16 v[72:75], v[126:129], v[122:125], v[72:75]
	ds_read_b128 v[126:129], v243 offset:2304
	s_waitcnt lgkmcnt(0)
	v_mfma_f32_16x16x32_bf16 v[68:71], v[126:129], v[76:79], v[68:71]
	ds_read_b128 v[126:129], v243 offset:2368
	v_add_u32_e32 v111, 0x1000, v81
	s_waitcnt lgkmcnt(0)
	v_mfma_f32_16x16x32_bf16 v[68:71], v[126:129], v[122:125], v[68:71]
	ds_read_b128 v[126:129], v243 offset:4608
	s_waitcnt lgkmcnt(0)
	v_mfma_f32_16x16x32_bf16 v[64:67], v[126:129], v[76:79], v[64:67]
	ds_read_b128 v[126:129], v243 offset:4672
	v_add_u32_e32 v111, 0x1800, v81
	s_waitcnt lgkmcnt(0)
	v_mfma_f32_16x16x32_bf16 v[64:67], v[126:129], v[122:125], v[64:67]
	ds_read_b128 v[126:129], v243 offset:6912
	s_waitcnt lgkmcnt(0)
	v_mfma_f32_16x16x32_bf16 v[60:63], v[126:129], v[76:79], v[60:63]
	ds_read_b128 v[76:79], v243 offset:6976
	s_waitcnt lgkmcnt(0)
	v_mfma_f32_16x16x32_bf16 v[60:63], v[76:79], v[122:125], v[60:63]

.LBB0_980:
	v_sub_f32_e32 v72, v72, v106
	v_exp_f32_e32 v72, v72
	v_sub_f32_e32 v73, v73, v106
	v_exp_f32_e32 v73, v73
	v_sub_f32_e32 v74, v74, v106
	v_exp_f32_e32 v74, v74
	v_sub_f32_e32 v75, v75, v106
	v_exp_f32_e32 v75, v75
	v_sub_f32_e32 v68, v68, v106
	v_add_f32_e32 v76, 0, v72
	v_exp_f32_e32 v68, v68
	v_sub_f32_e32 v69, v69, v106
	v_add_f32_e32 v76, v73, v76
	v_exp_f32_e32 v69, v69
	v_sub_f32_e32 v70, v70, v106
	v_add_f32_e32 v76, v74, v76
	v_exp_f32_e32 v70, v70
	v_sub_f32_e32 v71, v71, v106
	v_add_f32_e32 v76, v75, v76
	v_exp_f32_e32 v71, v71
	v_sub_f32_e32 v60, v60, v106
	v_add_f32_e32 v76, v68, v76
	v_exp_f32_e32 v60, v60
	v_sub_f32_e32 v61, v61, v106
	v_add_f32_e32 v76, v69, v76
	v_exp_f32_e32 v61, v61
	v_sub_f32_e32 v62, v62, v106
	v_add_f32_e32 v76, v70, v76
	v_exp_f32_e32 v62, v62
	v_sub_f32_e32 v63, v63, v106
	v_add_f32_e32 v108, v71, v76
	v_exp_f32_e32 v63, v63
	v_sub_f32_e32 v64, v64, v106
	v_cvt_pk_bf16_f32 v78, v68, v69
	v_add_f32_e32 v68, v60, v108
	v_exp_f32_e32 v64, v64
	v_sub_f32_e32 v65, v65, v106
	v_add_f32_e32 v68, v61, v68
	v_exp_f32_e32 v65, v65
	v_sub_f32_e32 v66, v66, v106
	v_add_f32_e32 v68, v62, v68
	v_exp_f32_e32 v66, v66
	v_sub_f32_e32 v67, v67, v106
	v_add_f32_e32 v68, v63, v68
	v_exp_f32_e32 v67, v67
	v_add_f32_e32 v68, v64, v68
	v_add_f32_e32 v68, v65, v68
	v_add_f32_e32 v68, v66, v68
	v_add_f32_e32 v68, v67, v68
	v_cvt_pk_bf16_f32 v60, v60, v61
	v_cvt_pk_bf16_f32 v61, v62, v63
	v_cvt_pk_bf16_f32 v62, v64, v65
	v_cvt_pk_bf16_f32 v63, v66, v67
	ds_read_b128 v[64:67], v243
	v_cvt_pk_bf16_f32 v76, v72, v73
	v_cvt_pk_bf16_f32 v77, v74, v75
	v_cvt_pk_bf16_f32 v79, v70, v71
	v_add_f32_e32 v110, v107, v68
	v_mov_b32_e32 v109, v106
	s_waitcnt lgkmcnt(0)
	v_mfma_f32_16x16x32_bf16 v[40:43], v[64:67], v[76:79], v[40:43]
	ds_read_b128 v[64:67], v243 offset:64
	s_waitcnt lgkmcnt(0)
	v_mfma_f32_16x16x32_bf16 v[72:75], v[64:67], v[60:63], v[40:43]
	v_add_u32_e32 v64, 0x800, v81
	s_nop 3
	ds_read_b128 v[40:43], v243 offset:2304
	s_waitcnt lgkmcnt(0)
	v_mfma_f32_16x16x32_bf16 v[36:39], v[40:43], v[76:79], v[36:39]
	ds_read_b128 v[40:43], v243 offset:2368
	s_waitcnt lgkmcnt(0)
	v_mfma_f32_16x16x32_bf16 v[68:71], v[40:43], v[60:63], v[36:39]
	v_add_u32_e32 v40, 0x1000, v81
	s_nop 3
	ds_read_b128 v[36:39], v243 offset:4608
	s_waitcnt lgkmcnt(0)
	v_mfma_f32_16x16x32_bf16 v[32:35], v[36:39], v[76:79], v[32:35]
	ds_read_b128 v[36:39], v243 offset:4672
	s_waitcnt lgkmcnt(0)
	v_mfma_f32_16x16x32_bf16 v[64:67], v[36:39], v[60:63], v[32:35]
	v_add_u32_e32 v36, 0x1800, v81
	s_nop 3
	ds_read_b128 v[32:35], v243 offset:6912
	s_waitcnt lgkmcnt(0)
	v_mfma_f32_16x16x32_bf16 v[28:31], v[32:35], v[76:79], v[28:31]
	ds_read_b128 v[32:35], v243 offset:6976
	s_waitcnt lgkmcnt(0)
	v_mfma_f32_16x16x32_bf16 v[60:63], v[32:35], v[60:63], v[28:31]

.LBB0_982:
	s_add_i32 s2, s16, 1
	s_cmp_lt_i32 s2, s11
	s_cselect_b64 s[4:5], -1, 0
	s_cmp_ge_i32 s2, s11
	s_cbranch_scc1 .LBB0_984
	s_waitcnt vmcnt(1)
	ds_write_b128 v113, v[52:55]
	s_waitcnt vmcnt(0)
	ds_write2_b64 v242, v[56:57], v[58:59] offset1:2

.LBB0_991:
	v_cmp_lt_f32_e32 vcc, s37, v76
	v_sub_f32_e32 v76, v76, v109
	v_exp_f32_e32 v76, v76
	s_mov_b64 s[4:5], 0
	v_cndmask_b32_e32 v76, 0, v76, vcc
	v_cmp_lt_f32_e32 vcc, s37, v77
	v_sub_f32_e32 v77, v77, v109
	v_exp_f32_e32 v77, v77
	v_add_f32_e32 v132, 0, v76
	v_cndmask_b32_e32 v77, 0, v77, vcc
	v_cmp_lt_f32_e32 vcc, s37, v78
	v_sub_f32_e32 v78, v78, v109
	v_exp_f32_e32 v78, v78
	v_add_f32_e32 v132, v77, v132
	v_cvt_pk_bf16_f32 v76, v76, v77
	v_cndmask_b32_e32 v78, 0, v78, vcc
	v_cmp_lt_f32_e32 vcc, s37, v79
	v_sub_f32_e32 v79, v79, v109
	v_exp_f32_e32 v79, v79
	v_add_f32_e32 v132, v78, v132
	v_cndmask_b32_e32 v79, 0, v79, vcc
	v_cmp_lt_f32_e32 vcc, s37, v110
	v_sub_f32_e32 v110, v110, v109
	v_exp_f32_e32 v110, v110
	v_add_f32_e32 v132, v79, v132
	v_cvt_pk_bf16_f32 v77, v78, v79
	v_cndmask_b32_e32 v110, 0, v110, vcc
	v_cmp_lt_f32_e32 vcc, s37, v111
	v_sub_f32_e32 v111, v111, v109
	v_exp_f32_e32 v111, v111
	v_add_f32_e32 v132, v110, v132
	v_cndmask_b32_e32 v111, 0, v111, vcc
	v_cmp_lt_f32_e32 vcc, s37, v121
	v_sub_f32_e32 v121, v121, v109
	v_exp_f32_e32 v121, v121
	v_add_f32_e32 v132, v111, v132
	v_cvt_pk_bf16_f32 v78, v110, v111
	v_sub_f32_e32 v110, v123, v109
	v_cndmask_b32_e32 v121, 0, v121, vcc
	v_cmp_lt_f32_e32 vcc, s37, v122
	v_sub_f32_e32 v122, v122, v109
	v_exp_f32_e32 v122, v122
	v_add_f32_e32 v132, v121, v132
	v_exp_f32_e32 v110, v110
	v_cndmask_b32_e32 v122, 0, v122, vcc
	v_cvt_pk_bf16_f32 v79, v121, v122
	v_sub_f32_e32 v121, v124, v109
	v_add_f32_e32 v132, v122, v132
	v_exp_f32_e32 v121, v121
	v_sub_f32_e32 v122, v125, v109
	v_exp_f32_e32 v122, v122
	v_cmp_lt_f32_e32 vcc, s37, v123
	s_nop 1
	v_cndmask_b32_e32 v110, 0, v110, vcc
	v_cmp_lt_f32_e32 vcc, s37, v124
	v_add_f32_e32 v111, v110, v132
	s_nop 0
	v_cndmask_b32_e32 v121, 0, v121, vcc
	v_cmp_lt_f32_e32 vcc, s37, v125
	v_add_f32_e32 v111, v121, v111
	s_nop 0
	v_cndmask_b32_e32 v123, 0, v122, vcc
	v_sub_f32_e32 v122, v126, v109
	v_exp_f32_e32 v122, v122
	v_cmp_lt_f32_e32 vcc, s37, v126
	v_add_f32_e32 v111, v123, v111
	s_nop 0
	v_cndmask_b32_e32 v124, 0, v122, vcc
	v_sub_f32_e32 v122, v127, v109
	v_exp_f32_e32 v122, v122
	v_cmp_lt_f32_e32 vcc, s37, v127
	v_add_f32_e32 v111, v124, v111
	v_cvt_pk_bf16_f32 v123, v123, v124
	v_cndmask_b32_e32 v125, 0, v122, vcc
	v_sub_f32_e32 v122, v128, v109
	v_exp_f32_e32 v122, v122
	v_cmp_lt_f32_e32 vcc, s37, v128
	v_add_f32_e32 v111, v125, v111
	s_nop 0
	v_cndmask_b32_e32 v126, 0, v122, vcc
	v_sub_f32_e32 v122, v129, v109
	v_exp_f32_e32 v122, v122
	v_cmp_lt_f32_e32 vcc, s37, v129
	v_add_f32_e32 v111, v126, v111
	v_cvt_pk_bf16_f32 v124, v125, v126
	v_cndmask_b32_e32 v127, 0, v122, vcc
	v_sub_f32_e32 v122, v130, v109
	v_exp_f32_e32 v122, v122
	v_cmp_lt_f32_e32 vcc, s37, v130
	v_add_f32_e32 v111, v127, v111
	s_nop 0
	v_cndmask_b32_e32 v128, 0, v122, vcc
	v_add_f32_e32 v111, v128, v111
	v_cvt_pk_bf16_f32 v125, v127, v128
	ds_read_b128 v[126:129], v244
	s_waitcnt lgkmcnt(0)
	v_mfma_f32_16x16x32_bf16 v[72:75], v[126:129], v[76:79], v[72:75]
	ds_read_b128 v[126:129], v244 offset:64
	v_cvt_pk_bf16_f32 v122, v110, v121
	v_add_f32_e32 v110, v131, v111
	v_add_u32_e32 v111, 0x800, v104
	s_waitcnt lgkmcnt(0)
	v_mfma_f32_16x16x32_bf16 v[72:75], v[126:129], v[122:125], v[72:75]
	ds_read_b128 v[126:129], v244 offset:2304
	s_waitcnt lgkmcnt(0)
	v_mfma_f32_16x16x32_bf16 v[68:71], v[126:129], v[76:79], v[68:71]
	ds_read_b128 v[126:129], v244 offset:2368
	v_add_u32_e32 v111, 0x1000, v104
	s_waitcnt lgkmcnt(0)
	v_mfma_f32_16x16x32_bf16 v[68:71], v[126:129], v[122:125], v[68:71]
	ds_read_b128 v[126:129], v244 offset:4608
	s_waitcnt lgkmcnt(0)
	v_mfma_f32_16x16x32_bf16 v[64:67], v[126:129], v[76:79], v[64:67]
	ds_read_b128 v[126:129], v244 offset:4672
	v_add_u32_e32 v111, 0x1800, v104
	s_waitcnt lgkmcnt(0)
	v_mfma_f32_16x16x32_bf16 v[64:67], v[126:129], v[122:125], v[64:67]
	ds_read_b128 v[126:129], v244 offset:6912
	s_waitcnt lgkmcnt(0)
	v_mfma_f32_16x16x32_bf16 v[60:63], v[126:129], v[76:79], v[60:63]
	ds_read_b128 v[76:79], v244 offset:6976
	s_waitcnt lgkmcnt(0)
	v_mfma_f32_16x16x32_bf16 v[60:63], v[76:79], v[122:125], v[60:63]

.LBB0_995:
	v_sub_f32_e32 v72, v72, v106
	v_exp_f32_e32 v72, v72
	v_sub_f32_e32 v73, v73, v106
	v_exp_f32_e32 v73, v73
	v_sub_f32_e32 v74, v74, v106
	v_exp_f32_e32 v74, v74
	v_sub_f32_e32 v75, v75, v106
	v_exp_f32_e32 v75, v75
	v_sub_f32_e32 v68, v68, v106
	v_add_f32_e32 v76, 0, v72
	v_exp_f32_e32 v68, v68
	v_sub_f32_e32 v69, v69, v106
	v_add_f32_e32 v76, v73, v76
	v_exp_f32_e32 v69, v69
	v_sub_f32_e32 v70, v70, v106
	v_add_f32_e32 v76, v74, v76
	v_exp_f32_e32 v70, v70
	v_sub_f32_e32 v71, v71, v106
	v_add_f32_e32 v76, v75, v76
	v_exp_f32_e32 v71, v71
	v_sub_f32_e32 v60, v60, v106
	v_add_f32_e32 v76, v68, v76
	v_exp_f32_e32 v60, v60
	v_sub_f32_e32 v61, v61, v106
	v_add_f32_e32 v76, v69, v76
	v_exp_f32_e32 v61, v61
	v_sub_f32_e32 v62, v62, v106
	v_add_f32_e32 v76, v70, v76
	v_exp_f32_e32 v62, v62
	v_sub_f32_e32 v63, v63, v106
	v_add_f32_e32 v108, v71, v76
	v_exp_f32_e32 v63, v63
	v_sub_f32_e32 v64, v64, v106
	v_cvt_pk_bf16_f32 v78, v68, v69
	v_add_f32_e32 v68, v60, v108
	v_exp_f32_e32 v64, v64
	v_sub_f32_e32 v65, v65, v106
	v_add_f32_e32 v68, v61, v68
	v_exp_f32_e32 v65, v65
	v_sub_f32_e32 v66, v66, v106
	v_add_f32_e32 v68, v62, v68
	v_exp_f32_e32 v66, v66
	v_sub_f32_e32 v67, v67, v106
	v_add_f32_e32 v68, v63, v68
	v_exp_f32_e32 v67, v67
	v_add_f32_e32 v68, v64, v68
	v_add_f32_e32 v68, v65, v68
	v_add_f32_e32 v68, v66, v68
	v_add_f32_e32 v68, v67, v68
	v_cvt_pk_bf16_f32 v60, v60, v61
	v_cvt_pk_bf16_f32 v61, v62, v63
	v_cvt_pk_bf16_f32 v62, v64, v65
	v_cvt_pk_bf16_f32 v63, v66, v67
	ds_read_b128 v[64:67], v244
	v_cvt_pk_bf16_f32 v76, v72, v73
	v_cvt_pk_bf16_f32 v77, v74, v75
	v_cvt_pk_bf16_f32 v79, v70, v71
	v_add_f32_e32 v110, v107, v68
	v_mov_b32_e32 v109, v106
	s_waitcnt lgkmcnt(0)
	v_mfma_f32_16x16x32_bf16 v[40:43], v[64:67], v[76:79], v[40:43]
	ds_read_b128 v[64:67], v244 offset:64
	s_waitcnt lgkmcnt(0)
	v_mfma_f32_16x16x32_bf16 v[72:75], v[64:67], v[60:63], v[40:43]
	v_add_u32_e32 v64, 0x800, v104
	s_nop 3
	ds_read_b128 v[40:43], v244 offset:2304
	s_waitcnt lgkmcnt(0)
	v_mfma_f32_16x16x32_bf16 v[36:39], v[40:43], v[76:79], v[36:39]
	ds_read_b128 v[40:43], v244 offset:2368
	s_waitcnt lgkmcnt(0)
	v_mfma_f32_16x16x32_bf16 v[68:71], v[40:43], v[60:63], v[36:39]
	v_add_u32_e32 v40, 0x1000, v104
	s_nop 3
	ds_read_b128 v[36:39], v244 offset:4608
	s_waitcnt lgkmcnt(0)
	v_mfma_f32_16x16x32_bf16 v[32:35], v[36:39], v[76:79], v[32:35]
	ds_read_b128 v[36:39], v244 offset:4672
	s_waitcnt lgkmcnt(0)
	v_mfma_f32_16x16x32_bf16 v[64:67], v[36:39], v[60:63], v[32:35]
	v_add_u32_e32 v36, 0x1800, v104
	s_nop 3
	ds_read_b128 v[32:35], v244 offset:6912
	s_waitcnt lgkmcnt(0)
	v_mfma_f32_16x16x32_bf16 v[28:31], v[32:35], v[76:79], v[28:31]
	ds_read_b128 v[32:35], v244 offset:6976
	s_waitcnt lgkmcnt(0)
	v_mfma_f32_16x16x32_bf16 v[60:63], v[32:35], v[60:63], v[28:31]

.LBB0_997:
	s_andn2_b64 vcc, exec, s[6:7]
	s_cbranch_vccnz .LBB0_999
	s_waitcnt vmcnt(1)
	ds_write_b128 v112, v[44:47]
	s_waitcnt vmcnt(0)
	ds_write2_b64 v238, v[48:49], v[50:51] offset1:2

.LBB0_1013:
	v_sub_f32_e32 v143, v3, v0
	v_exp_f32_e32 v143, v143
	v_sub_f32_e32 v144, v130, v0
	v_exp_f32_e32 v144, v144
	v_cmp_lt_f32_e32 vcc, s37, v3
	v_sub_f32_e32 v145, v135, v0
	v_exp_f32_e32 v145, v145
	v_cndmask_b32_e32 v3, 0, v143, vcc
	v_cmp_lt_f32_e32 vcc, s37, v130
	v_add_u32_e32 v159, 0x800, v123
	s_nop 0
	v_cndmask_b32_e32 v130, 0, v144, vcc
	v_sub_f32_e32 v144, v128, v0
	v_exp_f32_e32 v144, v144
	v_cmp_lt_f32_e32 vcc, s37, v128
	v_add_f32_e32 v143, 0, v130
	v_add_f32_e32 v143, v3, v143
	v_cndmask_b32_e32 v128, 0, v144, vcc
	v_cmp_lt_f32_e32 vcc, s37, v135
	v_sub_f32_e32 v144, v129, v0
	v_exp_f32_e32 v144, v144
	v_cndmask_b32_e32 v135, 0, v145, vcc
	v_sub_f32_e32 v145, v137, v0
	v_exp_f32_e32 v145, v145
	v_cmp_lt_f32_e32 vcc, s37, v129
	v_add_f32_e32 v143, v135, v143
	v_add_f32_e32 v143, v128, v143
	v_cndmask_b32_e32 v148, 0, v144, vcc
	v_cmp_lt_f32_e32 vcc, s37, v137
	v_sub_f32_e32 v137, v134, v0
	v_exp_f32_e32 v137, v137
	v_cndmask_b32_e32 v129, 0, v145, vcc
	v_add_f32_e32 v149, v129, v143
	v_sub_f32_e32 v143, v140, v0
	v_exp_f32_e32 v143, v143
	v_cvt_pk_bf16_f32 v144, v130, v3
	v_sub_f32_e32 v3, v131, v0
	v_cvt_pk_bf16_f32 v145, v135, v128
	v_exp_f32_e32 v3, v3
	v_sub_f32_e32 v128, v139, v0
	v_cmp_lt_f32_e32 vcc, s37, v134
	v_exp_f32_e32 v128, v128
	v_cvt_pk_bf16_f32 v146, v129, v148
	v_cndmask_b32_e32 v150, 0, v137, vcc
	v_cmp_lt_f32_e32 vcc, s37, v140
	v_sub_f32_e32 v129, v141, v0
	v_exp_f32_e32 v129, v129
	v_cndmask_b32_e32 v151, 0, v143, vcc
	v_cmp_lt_f32_e32 vcc, s37, v131
	v_cvt_pk_bf16_f32 v147, v151, v150
	v_add_f32_e32 v148, v148, v149
	v_cndmask_b32_e32 v3, 0, v3, vcc
	v_cmp_lt_f32_e32 vcc, s37, v139
	v_add_u32_e32 v149, 0x1000, v123
	s_nop 0
	v_cndmask_b32_e32 v152, 0, v128, vcc
	v_sub_f32_e32 v128, v136, v0
	v_exp_f32_e32 v128, v128
	v_cmp_lt_f32_e32 vcc, s37, v136
	v_cvt_pk_bf16_f32 v136, v152, v3
	s_nop 0
	v_cndmask_b32_e32 v153, 0, v128, vcc
	v_cmp_lt_f32_e32 vcc, s37, v141
	v_sub_f32_e32 v128, v138, v0
	v_exp_f32_e32 v128, v128
	v_cndmask_b32_e32 v154, 0, v129, vcc
	v_sub_f32_e32 v129, v142, v0
	v_exp_f32_e32 v129, v129
	v_cmp_lt_f32_e32 vcc, s37, v138
	v_cvt_pk_bf16_f32 v137, v154, v153
	s_nop 0
	v_cndmask_b32_e32 v155, 0, v128, vcc
	v_cmp_lt_f32_e32 vcc, s37, v142
	v_sub_f32_e32 v128, v132, v0
	v_exp_f32_e32 v135, v128
	v_cndmask_b32_e32 v156, 0, v129, vcc
	v_sub_f32_e32 v129, v133, v0
	v_exp_f32_e32 v134, v129
	ds_read_b128 v[128:131], v243
	v_cmp_lt_f32_e32 vcc, s37, v133
	ds_read_b128 v[140:143], v243 offset:2304
	s_waitcnt lgkmcnt(1)
	v_mfma_f32_16x16x32_bf16 v[76:79], v[128:131], v[144:147], v[76:79]
	v_cndmask_b32_e32 v157, 0, v134, vcc
	v_cmp_lt_f32_e32 vcc, s37, v132
	ds_read_b128 v[128:131], v243 offset:2368
	v_cvt_pk_bf16_f32 v138, v156, v155
	v_cndmask_b32_e32 v158, 0, v135, vcc
	ds_read_b128 v[132:135], v243 offset:64
	v_cvt_pk_bf16_f32 v139, v158, v157
	s_waitcnt lgkmcnt(2)
	v_mfma_f32_16x16x32_bf16 v[80:83], v[140:143], v[144:147], v[80:83]
	v_add_f32_e32 v140, v151, v148
	v_add_f32_e32 v148, v150, v140
	ds_read_b128 v[140:143], v243 offset:4672
	s_waitcnt lgkmcnt(1)
	v_mfma_f32_16x16x32_bf16 v[76:79], v[132:135], v[136:139], v[76:79]
	ds_read_b128 v[132:135], v243 offset:4608
	v_add_u32_e32 v149, 0x1800, v123
	v_add_f32_e32 v148, v152, v148
	v_mfma_f32_16x16x32_bf16 v[80:83], v[128:131], v[136:139], v[80:83]
	ds_read_b128 v[128:131], v243 offset:6912
	v_add_f32_e32 v3, v3, v148
	v_add_f32_e32 v3, v154, v3
	s_waitcnt lgkmcnt(1)
	v_mfma_f32_16x16x32_bf16 v[84:87], v[132:135], v[144:147], v[84:87]
	ds_read_b128 v[132:135], v243 offset:6976
	v_add_f32_e32 v3, v153, v3
	v_add_f32_e32 v3, v156, v3
	s_waitcnt lgkmcnt(1)
	v_mfma_f32_16x16x32_bf16 v[88:91], v[128:131], v[144:147], v[88:91]
	v_add_f32_e32 v3, v155, v3
	v_add_f32_e32 v3, v158, v3
	v_add_f32_e32 v3, v157, v3
	v_mfma_f32_16x16x32_bf16 v[84:87], v[140:143], v[136:139], v[84:87]
	v_add_f32_e32 v2, v2, v3
	s_waitcnt lgkmcnt(0)
	v_mfma_f32_16x16x32_bf16 v[88:91], v[132:135], v[136:139], v[88:91]

.LBB0_1015:
	s_waitcnt vmcnt(1)
	ds_write_b128 v113, v[52:55]
	s_waitcnt vmcnt(0)
	ds_write2_b64 v242, v[56:57], v[58:59] offset1:2

.LBB0_1022:
	v_sub_f32_e32 v143, v127, v126
	v_exp_f32_e32 v143, v143
	v_sub_f32_e32 v144, v130, v126
	v_exp_f32_e32 v144, v144
	v_cmp_lt_f32_e32 vcc, s37, v127
	v_sub_f32_e32 v145, v135, v126
	v_exp_f32_e32 v145, v145
	v_cndmask_b32_e32 v127, 0, v143, vcc
	v_cmp_lt_f32_e32 vcc, s37, v130
	v_add_u32_e32 v159, 0x800, v124
	s_nop 0
	v_cndmask_b32_e32 v130, 0, v144, vcc
	v_sub_f32_e32 v144, v128, v126
	v_exp_f32_e32 v144, v144
	v_cmp_lt_f32_e32 vcc, s37, v128
	v_add_f32_e32 v143, 0, v130
	v_add_f32_e32 v143, v127, v143
	v_cndmask_b32_e32 v128, 0, v144, vcc
	v_cmp_lt_f32_e32 vcc, s37, v135
	v_sub_f32_e32 v144, v129, v126
	v_exp_f32_e32 v144, v144
	v_cndmask_b32_e32 v135, 0, v145, vcc
	v_sub_f32_e32 v145, v137, v126
	v_exp_f32_e32 v145, v145
	v_cmp_lt_f32_e32 vcc, s37, v129
	v_add_f32_e32 v143, v135, v143
	v_add_f32_e32 v143, v128, v143
	v_cndmask_b32_e32 v148, 0, v144, vcc
	v_cmp_lt_f32_e32 vcc, s37, v137
	v_sub_f32_e32 v137, v134, v126
	v_exp_f32_e32 v137, v137
	v_cndmask_b32_e32 v129, 0, v145, vcc
	v_add_f32_e32 v149, v129, v143
	v_sub_f32_e32 v143, v140, v126
	v_exp_f32_e32 v143, v143
	v_cvt_pk_bf16_f32 v144, v130, v127
	v_sub_f32_e32 v127, v131, v126
	v_cvt_pk_bf16_f32 v145, v135, v128
	v_exp_f32_e32 v127, v127
	v_sub_f32_e32 v128, v139, v126
	v_cmp_lt_f32_e32 vcc, s37, v134
	v_exp_f32_e32 v128, v128
	v_cvt_pk_bf16_f32 v146, v129, v148
	v_cndmask_b32_e32 v150, 0, v137, vcc
	v_cmp_lt_f32_e32 vcc, s37, v140
	v_sub_f32_e32 v129, v141, v126
	v_exp_f32_e32 v129, v129
	v_cndmask_b32_e32 v151, 0, v143, vcc
	v_cmp_lt_f32_e32 vcc, s37, v131
	v_cvt_pk_bf16_f32 v147, v151, v150
	v_add_f32_e32 v148, v148, v149
	v_cndmask_b32_e32 v127, 0, v127, vcc
	v_cmp_lt_f32_e32 vcc, s37, v139
	v_add_u32_e32 v149, 0x1000, v124
	s_nop 0
	v_cndmask_b32_e32 v152, 0, v128, vcc
	v_sub_f32_e32 v128, v136, v126
	v_exp_f32_e32 v128, v128
	v_cmp_lt_f32_e32 vcc, s37, v136
	v_cvt_pk_bf16_f32 v136, v152, v127
	s_nop 0
	v_cndmask_b32_e32 v153, 0, v128, vcc
	v_cmp_lt_f32_e32 vcc, s37, v141
	v_sub_f32_e32 v128, v138, v126
	v_exp_f32_e32 v128, v128
	v_cndmask_b32_e32 v154, 0, v129, vcc
	v_sub_f32_e32 v129, v142, v126
	v_exp_f32_e32 v129, v129
	v_cmp_lt_f32_e32 vcc, s37, v138
	v_cvt_pk_bf16_f32 v137, v154, v153
	s_nop 0
	v_cndmask_b32_e32 v155, 0, v128, vcc
	v_cmp_lt_f32_e32 vcc, s37, v142
	v_sub_f32_e32 v128, v132, v126
	v_exp_f32_e32 v135, v128
	v_cndmask_b32_e32 v156, 0, v129, vcc
	v_sub_f32_e32 v129, v133, v126
	v_exp_f32_e32 v134, v129
	ds_read_b128 v[128:131], v244
	v_cmp_lt_f32_e32 vcc, s37, v133
	ds_read_b128 v[140:143], v244 offset:2304
	s_waitcnt lgkmcnt(1)
	v_mfma_f32_16x16x32_bf16 v[60:63], v[128:131], v[144:147], v[60:63]
	v_cndmask_b32_e32 v157, 0, v134, vcc
	v_cmp_lt_f32_e32 vcc, s37, v132
	ds_read_b128 v[128:131], v244 offset:2368
	v_cvt_pk_bf16_f32 v138, v156, v155
	v_cndmask_b32_e32 v158, 0, v135, vcc
	ds_read_b128 v[132:135], v244 offset:64
	v_cvt_pk_bf16_f32 v139, v158, v157
	s_waitcnt lgkmcnt(2)
	v_mfma_f32_16x16x32_bf16 v[64:67], v[140:143], v[144:147], v[64:67]
	v_add_f32_e32 v140, v151, v148
	v_add_f32_e32 v148, v150, v140
	ds_read_b128 v[140:143], v244 offset:4672
	s_waitcnt lgkmcnt(1)
	v_mfma_f32_16x16x32_bf16 v[60:63], v[132:135], v[136:139], v[60:63]
	ds_read_b128 v[132:135], v244 offset:4608
	v_add_u32_e32 v149, 0x1800, v124
	v_add_f32_e32 v148, v152, v148
	v_mfma_f32_16x16x32_bf16 v[64:67], v[128:131], v[136:139], v[64:67]
	ds_read_b128 v[128:131], v244 offset:6912
	v_add_f32_e32 v127, v127, v148
	v_add_f32_e32 v127, v154, v127
	s_waitcnt lgkmcnt(1)
	v_mfma_f32_16x16x32_bf16 v[68:71], v[132:135], v[144:147], v[68:71]
	ds_read_b128 v[132:135], v244 offset:6976
	v_add_f32_e32 v127, v153, v127
	v_add_f32_e32 v127, v156, v127
	s_waitcnt lgkmcnt(1)
	v_mfma_f32_16x16x32_bf16 v[72:75], v[128:131], v[144:147], v[72:75]
	v_add_f32_e32 v127, v155, v127
	v_add_f32_e32 v127, v158, v127
	v_add_f32_e32 v127, v157, v127
	v_mfma_f32_16x16x32_bf16 v[68:71], v[140:143], v[136:139], v[68:71]
	v_add_f32_e32 v127, v3, v127
	s_waitcnt lgkmcnt(0)
	v_mfma_f32_16x16x32_bf16 v[72:75], v[132:135], v[136:139], v[72:75]

.LBB0_1027:
	v_sub_f32_e32 v0, v88, v126
	v_exp_f32_e32 v0, v0
	v_sub_f32_e32 v3, v89, v126
	v_exp_f32_e32 v3, v3
	v_sub_f32_e32 v88, v90, v126
	v_exp_f32_e32 v88, v88
	v_sub_f32_e32 v89, v91, v126
	v_exp_f32_e32 v89, v89
	v_sub_f32_e32 v84, v84, v126
	v_add_f32_e32 v2, 0, v0
	v_exp_f32_e32 v84, v84
	v_sub_f32_e32 v85, v85, v126
	v_add_f32_e32 v2, v3, v2
	v_exp_f32_e32 v85, v85
	v_sub_f32_e32 v86, v86, v126
	v_add_f32_e32 v2, v88, v2
	v_exp_f32_e32 v86, v86
	v_sub_f32_e32 v87, v87, v126
	v_add_f32_e32 v2, v89, v2
	v_exp_f32_e32 v87, v87
	v_cvt_pk_bf16_f32 v128, v0, v3
	v_sub_f32_e32 v0, v76, v126
	v_add_f32_e32 v2, v84, v2
	v_exp_f32_e32 v0, v0
	v_sub_f32_e32 v3, v77, v126
	v_add_f32_e32 v2, v85, v2
	v_exp_f32_e32 v3, v3
	v_sub_f32_e32 v76, v78, v126
	v_add_f32_e32 v2, v86, v2
	v_exp_f32_e32 v76, v76
	v_sub_f32_e32 v77, v79, v126
	v_add_f32_e32 v2, v87, v2
	v_exp_f32_e32 v77, v77
	v_sub_f32_e32 v78, v80, v126
	v_add_f32_e32 v2, v0, v2
	v_exp_f32_e32 v78, v78
	v_sub_f32_e32 v79, v81, v126
	v_add_f32_e32 v2, v3, v2
	v_exp_f32_e32 v79, v79
	v_add_f32_e32 v2, v76, v2
	v_add_f32_e32 v2, v77, v2
	v_add_f32_e32 v2, v78, v2
	v_cvt_pk_bf16_f32 v129, v88, v89
	v_add_f32_e32 v2, v79, v2
	v_cvt_pk_bf16_f32 v89, v76, v77
	v_cvt_pk_bf16_f32 v90, v78, v79
	ds_read_b128 v[76:79], v243
	v_cvt_pk_bf16_f32 v130, v84, v85
	v_cvt_pk_bf16_f32 v131, v86, v87
	v_sub_f32_e32 v80, v82, v126
	v_sub_f32_e32 v81, v83, v126
	s_waitcnt lgkmcnt(0)
	v_mfma_f32_16x16x32_bf16 v[60:63], v[76:79], v[128:131], v[60:63]
	ds_read_b128 v[76:79], v243 offset:64
	v_exp_f32_e32 v80, v80
	v_exp_f32_e32 v81, v81
	v_cvt_pk_bf16_f32 v88, v0, v3
	v_add_u32_e32 v0, 0x800, v123
	v_add_f32_e32 v2, v80, v2
	v_cvt_pk_bf16_f32 v91, v80, v81
	v_add_f32_e32 v2, v81, v2
	v_add_f32_e32 v2, v127, v2
	s_waitcnt lgkmcnt(0)
	v_mfma_f32_16x16x32_bf16 v[76:79], v[76:79], v[88:91], v[60:63]
	s_nop 2
	ds_read_b128 v[60:63], v243 offset:2304
	s_waitcnt lgkmcnt(0)
	v_mfma_f32_16x16x32_bf16 v[60:63], v[60:63], v[128:131], v[64:67]
	s_nop 2
	ds_read_b128 v[64:67], v243 offset:2368
	v_add_u32_e32 v0, 0x1000, v123
	s_waitcnt lgkmcnt(0)
	v_mfma_f32_16x16x32_bf16 v[80:83], v[64:67], v[88:91], v[60:63]
	s_nop 2
	ds_read_b128 v[60:63], v243 offset:4608
	ds_read_b128 v[64:67], v243 offset:4672
	v_add_u32_e32 v0, 0x1800, v123
	s_waitcnt lgkmcnt(1)
	v_mfma_f32_16x16x32_bf16 v[60:63], v[60:63], v[128:131], v[68:71]
	s_waitcnt lgkmcnt(0)
	v_mfma_f32_16x16x32_bf16 v[84:87], v[64:67], v[88:91], v[60:63]
	ds_read_b128 v[64:67], v243 offset:6976
	s_nop 4
	ds_read_b128 v[60:63], v243 offset:6912
	s_waitcnt lgkmcnt(0)
	v_mfma_f32_16x16x32_bf16 v[60:63], v[60:63], v[128:131], v[72:75]
	v_mov_b32_e32 v0, v126
	v_mfma_f32_16x16x32_bf16 v[88:91], v[64:67], v[88:91], v[60:63]
	s_cmp_lt_i32 s17, s11
	s_cselect_b64 s[4:5], -1, 0
	s_cmp_ge_i32 s17, s11
	s_cbranch_scc0 .LBB0_1015
	s_branch .LBB0_1016

.LBB0_1032:
	v_sub_f32_e32 v3, v72, v0
	v_exp_f32_e32 v3, v3
	v_sub_f32_e32 v73, v73, v0
	v_exp_f32_e32 v73, v73
	v_sub_f32_e32 v74, v74, v0
	v_exp_f32_e32 v74, v74
	v_sub_f32_e32 v75, v75, v0
	v_exp_f32_e32 v75, v75
	v_sub_f32_e32 v68, v68, v0
	v_add_f32_e32 v72, 0, v3
	v_exp_f32_e32 v68, v68
	v_sub_f32_e32 v69, v69, v0
	v_add_f32_e32 v72, v73, v72
	v_exp_f32_e32 v69, v69
	v_sub_f32_e32 v70, v70, v0
	v_add_f32_e32 v72, v74, v72
	v_exp_f32_e32 v70, v70
	v_sub_f32_e32 v71, v71, v0
	v_add_f32_e32 v72, v75, v72
	v_exp_f32_e32 v71, v71
	v_cvt_pk_bf16_f32 v128, v3, v73
	v_sub_f32_e32 v3, v60, v0
	v_add_f32_e32 v72, v68, v72
	v_exp_f32_e32 v3, v3
	v_sub_f32_e32 v61, v61, v0
	v_add_f32_e32 v72, v69, v72
	v_exp_f32_e32 v61, v61
	v_sub_f32_e32 v62, v62, v0
	v_add_f32_e32 v72, v70, v72
	v_exp_f32_e32 v62, v62
	v_sub_f32_e32 v63, v63, v0
	v_add_f32_e32 v72, v71, v72
	v_exp_f32_e32 v63, v63
	v_sub_f32_e32 v64, v64, v0
	v_add_f32_e32 v60, v3, v72
	v_exp_f32_e32 v64, v64
	v_sub_f32_e32 v65, v65, v0
	v_add_f32_e32 v60, v61, v60
	v_exp_f32_e32 v65, v65
	v_sub_f32_e32 v66, v66, v0
	v_add_f32_e32 v60, v62, v60
	v_exp_f32_e32 v66, v66
	v_sub_f32_e32 v67, v67, v0
	v_add_f32_e32 v60, v63, v60
	v_exp_f32_e32 v67, v67
	v_add_f32_e32 v60, v64, v60
	v_add_f32_e32 v60, v65, v60
	v_add_f32_e32 v60, v66, v60
	v_add_f32_e32 v60, v67, v60
	v_cvt_pk_bf16_f32 v72, v3, v61
	v_cvt_pk_bf16_f32 v73, v62, v63
	v_add_f32_e32 v127, v2, v60
	ds_read_b128 v[60:63], v244
	v_cvt_pk_bf16_f32 v129, v74, v75
	v_cvt_pk_bf16_f32 v74, v64, v65
	v_cvt_pk_bf16_f32 v75, v66, v67
	ds_read_b128 v[64:67], v244 offset:64
	v_cvt_pk_bf16_f32 v130, v68, v69
	v_cvt_pk_bf16_f32 v131, v70, v71
	v_add_u32_e32 v2, 0x800, v124
	ds_read_b128 v[68:71], v244 offset:2368
	s_waitcnt lgkmcnt(2)
	v_mfma_f32_16x16x32_bf16 v[60:63], v[60:63], v[128:131], v[76:79]
	v_mov_b32_e32 v126, v0
	s_waitcnt lgkmcnt(1)
	v_mfma_f32_16x16x32_bf16 v[60:63], v[64:67], v[72:75], v[60:63]
	ds_read_b128 v[64:67], v244 offset:2304
	v_add_u32_e32 v2, 0x1000, v124
	ds_read_b128 v[76:79], v244 offset:4672
	s_waitcnt lgkmcnt(1)
	v_mfma_f32_16x16x32_bf16 v[64:67], v[64:67], v[128:131], v[80:83]
	v_mfma_f32_16x16x32_bf16 v[64:67], v[68:71], v[72:75], v[64:67]
	ds_read_b128 v[68:71], v244 offset:4608
	v_add_u32_e32 v2, 0x1800, v124
	ds_read_b128 v[80:83], v244 offset:6976
	s_waitcnt lgkmcnt(1)
	v_mfma_f32_16x16x32_bf16 v[68:71], v[68:71], v[128:131], v[84:87]
	v_mfma_f32_16x16x32_bf16 v[68:71], v[76:79], v[72:75], v[68:71]
	ds_read_b128 v[76:79], v244 offset:6912
	s_waitcnt lgkmcnt(0)
	v_mfma_f32_16x16x32_bf16 v[76:79], v[76:79], v[128:131], v[88:91]
	v_mfma_f32_16x16x32_bf16 v[72:75], v[80:83], v[72:75], v[76:79]
	s_andn2_b64 vcc, exec, s[8:9]
	s_cbranch_vccnz .LBB0_1007
.LBB0_1033:
	s_waitcnt vmcnt(1)
	ds_write_b128 v112, v[44:47]
	s_waitcnt vmcnt(0)
	ds_write2_b64 v238, v[48:49], v[50:51] offset1:2
	s_branch .LBB0_1007
